# itemwait3: MIX3 hgrn-out item loop: loop-top full wait moved to the preheader (on the back edge it only waited for the output-store acks); on top of itemwait
# baseline (speedup 1.0000x reference)
.LBB0_81:
	v_lshrrev_b32_e32 v13, 2, v3
	v_bfe_u32 v14, v3, 2, 6
	v_bitop3_b32 v0, v13, 63, v13 bitop3:0xc
	v_readlane_b32 s14, v254, 41
	v_cndmask_b32_e64 v94, v0, v14, s[6:7]
	v_lshlrev_b32_e32 v0, 4, v3
	v_readlane_b32 s15, v254, 42
	v_and_b32_e32 v2, 48, v0
	v_mov_b32_e32 v0, 0x500
	v_mov_b32_e32 v4, 0x400
	s_lshl_b64 s[14:15], s[14:15], 2
	v_cndmask_b32_e64 v4, v0, v4, s[6:7]
	v_ashrrev_i32_e32 v0, 7, v3
	s_waitcnt lgkmcnt(0)
	s_add_u32 s16, s12, s14
	v_and_b32_e32 v95, -2, v0
	v_lshlrev_b32_e32 v0, 7, v14
	s_addc_u32 s17, s13, s15
	v_lshl_add_u64 v[8:9], s[48:49], 0, v[0:1]
	v_lshlrev_b32_e32 v10, 1, v2
	v_mov_b32_e32 v11, v1
	v_add_u32_e32 v7, s10, v95
	s_and_b32 s12, s19, 3
	v_lshl_add_u64 v[96:97], v[8:9], 0, v[10:11]
	v_lshl_or_b32 v8, v7, 2, s12
	v_ashrrev_i32_e32 v7, 31, v6
	s_movk_i32 s10, 0x84
	v_mad_i64_i32 v[6:7], s[10:11], v8, s10, v[6:7]
	v_lshlrev_b64 v[6:7], 13, v[6:7]
	v_writelane_b32 v255, s48, 0
	s_lshl_b32 s10, s18, 6
	s_ashr_i32 s11, s10, 31
	v_lshl_add_u64 v[6:7], s[48:49], 0, v[6:7]
	v_lshl_add_u64 v[6:7], v[6:7], 0, v[0:1]
	v_lshl_add_u64 v[6:7], v[6:7], 0, v[10:11]
	global_load_dwordx4 v[34:37], v[6:7], off offset:16
	global_load_dwordx4 v[38:41], v[6:7], off
	v_or_b32_e32 v6, s10, v94
	v_mov_b32_e32 v7, s11
	v_lshl_add_u64 v[6:7], v[6:7], 0, s[8:9]
	v_mov_b64_e32 v[8:9], s[82:83]
	v_mad_u64_u32 v[8:9], s[8:9], v6, s85, v[8:9]
	v_mov_b32_e32 v0, v9
	v_mad_u64_u32 v[6:7], s[8:9], v7, s85, v[0:1]
	v_mov_b32_e32 v9, v6
	s_lshl_b32 s80, s12, 7
	v_lshl_add_u64 v[6:7], v[8:9], 0, s[80:81]
	v_lshl_add_u64 v[6:7], v[6:7], 0, v[10:11]
	global_load_dwordx4 v[46:49], v[6:7], off offset:3088
	global_load_dwordx4 v[54:57], v[6:7], off offset:3072
	global_load_dwordx4 v[42:45], v[6:7], off offset:1552
	global_load_dwordx4 v[50:53], v[6:7], off offset:1536
	v_lshlrev_b32_e32 v0, 1, v4
	v_lshl_add_u64 v[6:7], v[6:7], 0, v[0:1]
	global_load_dwordx4 v[58:61], v[6:7], off offset:16
	global_load_dwordx4 v[62:65], v[6:7], off
	v_ashrrev_i32_e32 v0, 8, v3
	s_mov_b32 s8, 0xb400
	s_add_i32 s20, 0, 0x16800
	v_mad_i32_i24 v7, v0, s8, 0
	v_mov_b32_e32 v8, s20
	s_movk_i32 s8, 0x4400
	v_mad_i32_i24 v0, v0, s8, v8
	v_and_b32_e32 v8, 0x3fffff00, v3
	v_readlane_b32 s8, v254, 9
	v_lshlrev_b32_e32 v11, 2, v3
	v_and_b32_e32 v6, 0xff, v3
	v_lshl_add_u32 v8, v8, 2, s8
	v_and_b32_e32 v11, 0xfc, v11
	s_movk_i32 s14, 0x80
	v_lshl_add_u32 v124, v2, 2, v0
	v_add_u32_e32 v15, v0, v11
	v_add_u32_e32 v127, v8, v11
	v_cmp_gt_u32_e64 s[14:15], s14, v6
	v_mov_b32_e32 v0, 0x4800
	v_mov_b32_e32 v11, 0x5a00
	v_cndmask_b32_e64 v0, v0, v11, s[14:15]
	v_add_u32_e32 v11, v7, v0
	v_bfe_u32 v0, v6, 2, 5
	v_mul_u32_u24_e32 v16, 0x48, v0
	v_mul_u32_u24_e32 v0, 0x90, v14
	s_movk_i32 s10, 0x7f
	v_add3_u32 v128, v7, v0, v10
	v_lshlrev_b32_e32 v10, 3, v3
	v_lshl_add_u32 v126, v6, 2, v8
	v_cmp_gt_u32_e64 s[8:9], 64, v6
	v_cmp_lt_u32_e64 s[10:11], s10, v6
	v_and_b32_e32 v6, 56, v10
	v_lshlrev_b32_e32 v0, 2, v6
	v_lshl_add_u64 v[98:99], s[16:17], 0, v[0:1]
	s_lshr_b32 s16, s3, 8
	s_mul_i32 s16, s16, 0xb400
	v_and_b32_e32 v5, 31, v3
	s_bfe_u32 s22, s3, 0x10006
	s_add_i32 s18, s16, 0
	v_bfe_u32 v12, v3, 5, 1
	v_mad_u32_u24 v125, v14, s88, v124
	v_mul_u32_u24_e32 v8, 0x48, v14
	s_bfe_u32 s21, s3, 0x10007
	v_lshl_or_b32 v14, s22, 5, v5
	v_mov_b32_e32 v17, s18
	s_and_b32 s19, 64, s3
	v_mad_u32_u24 v14, v14, s89, v17
	v_lshlrev_b32_e32 v17, 4, v12
	s_cmp_eq_u32 s22, 0
	v_lshl_or_b32 v18, s21, 5, v5
	v_add_u32_e32 v19, s18, v17
	s_cselect_b64 s[16:17], -1, 0
	s_cmp_lg_u32 s19, 0
	v_mad_u32_u24 v130, v18, s89, v19
	s_cselect_b64 s[72:73], -1, 0
	v_mul_u32_u24_e32 v18, 0x90, v5
	s_lshl_b32 s19, s21, 6
	v_add3_u32 v131, s18, v18, v17
	s_add_i32 s18, s18, s19
	v_bfe_u32 v9, v3, 6, 2
	v_ashrrev_i32_e32 v129, 3, v3
	v_and_b32_e32 v3, 16, v3
	s_cmpk_lt_u32 s3, 0x100
	v_lshlrev_b32_e32 v3, 1, v3
	v_and_b32_e32 v10, 24, v10
	s_cselect_b64 vcc, -1, 0
	v_add3_u32 v3, s18, v3, v10
	s_and_b64 s[18:19], vcc, exec
	s_mov_b32 s3, 0x1a800
	s_cselect_b32 s3, 0x16800, s3
	s_lshl_b32 s18, s22, 11
	v_lshlrev_b32_e32 v10, 6, v5
	v_mov_b32_e32 v21, 0xfc0
	s_add_i32 s3, s3, 0
	v_or_b32_e32 v20, s18, v10
	v_bitop3_b32 v10, s18, v21, v10 bitop3:0x36
	s_lshl_b32 s18, s21, 7
	v_cndmask_b32_e32 v10, v10, v20, vcc
	s_add_i32 s18, s18, s3
	v_lshlrev_b32_e32 v20, 8, v129
	s_add_i32 s3, 0, 0x1a800
	v_mad_u32_u24 v134, v5, s89, v19
	v_cmp_eq_u32_e64 s[12:13], 3, v9
	v_add_u32_e32 v18, 0x5a00, v131
	v_lshlrev_b32_e32 v12, 2, v12
	v_add3_u32 v132, s20, v20, v0
	v_add3_u32 v133, s3, v20, v0
	v_mul_u32_u24_e32 v0, 0x1100, v9
	v_add_lshl_u32 v9, v16, v2, 1
	v_add_u32_e32 v16, 0x2400, v134
	v_cndmask_b32_e64 v135, v18, v16, s[16:17]
	v_or_b32_e32 v16, 2, v12
	v_cmp_gt_u32_e64 s[22:23], v16, v5
	v_or_b32_e32 v16, 3, v12
	v_cmp_gt_u32_e64 s[24:25], v16, v5
	v_or_b32_e32 v16, 8, v12
	v_cmp_gt_u32_e64 s[26:27], v16, v5
	v_or_b32_e32 v16, 9, v12
	v_cmp_gt_u32_e64 s[28:29], v16, v5
	v_or_b32_e32 v16, 10, v12
	v_cmp_gt_u32_e64 s[30:31], v16, v5
	v_or_b32_e32 v16, 11, v12
	v_cmp_gt_u32_e64 s[34:35], v16, v5
	v_or_b32_e32 v16, 16, v12
	v_cmp_gt_u32_e64 s[36:37], v16, v5
	v_or_b32_e32 v16, 17, v12
	v_cmp_gt_u32_e64 s[38:39], v16, v5
	v_or_b32_e32 v16, 18, v12
	v_cmp_gt_u32_e64 s[40:41], v16, v5
	v_or_b32_e32 v16, 19, v12
	v_cmp_gt_u32_e64 s[42:43], v16, v5
	v_or_b32_e32 v16, 24, v12
	v_cmp_gt_u32_e64 s[44:45], v16, v5
	v_or_b32_e32 v16, 25, v12
	v_and_or_b32 v13, v13, 3, v12
	v_lshl_add_u32 v10, v10, 2, s18
	v_cmp_gt_u32_e64 s[18:19], v12, v5
	v_cmp_lt_u32_e64 s[20:21], v12, v5
	v_cmp_gt_u32_e64 s[46:47], v16, v5
	v_or_b32_e32 v16, 26, v12
	v_or_b32_e32 v12, 27, v12
	v_writelane_b32 v255, s49, 1
	v_add_lshl_u32 v8, v8, v2, 1
	v_cmp_gt_u32_e64 s[48:49], v16, v5
	v_cmp_gt_u32_e64 s[50:51], v12, v5
	v_mul_u32_u24_e32 v5, 0x90, v13
	v_add_u32_e32 v136, v15, v0
	v_add_u32_e32 v137, v7, v8
	v_add_u32_e32 v138, v11, v9
	v_lshlrev_b32_e32 v0, 1, v6
	v_lshlrev_b32_e32 v100, 1, v2
	v_lshlrev_b32_e32 v102, 1, v4
	v_add_u32_e32 v139, v14, v17
	v_add_u32_e32 v140, v10, v17
	v_add_u32_e32 v141, v3, v5
	s_waitcnt vmcnt(0)
	s_branch .LBB0_83

.LBB0_91:
	s_cmp_eq_u32 s100, -1
	s_cbranch_scc1 .Lrga_skip
	s_lshr_b32 s98, s100, 1
	s_and_b32 s99, s100, 1
	v_mov_b32_e32 v160, s98
	v_mov_b32_e32 v161, s99
	s_cmp_eq_u64 s[4:5], 0
	s_cbranch_scc0 .Lrga_l1
	v_cmp_le_u32_e32 vcc, 0x84, v160
	s_nop 1
	v_cndmask_b32_e64 v162, 0, 1, vcc
	v_mul_u32_u24_e32 v163, 0x84, v162
	v_sub_u32_e32 v160, v160, v163
	s_branch .Lrga_dec
